# stack15: attention unit end fetches the 16 per-row normalisation factors with four ds_read_b128 and one wait instead of a serial ds_read_b32 ladder (on top of stack12)
# baseline (speedup 1.0000x reference)
; #define LDS_WAIT() asm volatile("s_waitcnt lgkmcnt(0)" ::: "memory")
; DI unsigned short f2bf(float f) { return (unsigned short)(pg8::cvt_pk_bf16(f, 0.f) & 0xffffu); }
; DI float half_sum(float x) { const auto rr = __builtin_amdgcn_permlane32_swap(__float_as_uint(x), __float_as_uint(x), false, false); return __uint_as_float(rr[0]) + __uint_as_float(rr[1]); }
; DI int crow(int r, int h) { return (r & 3) + 8 * (r >> 2) + 4 * h; }
; DI void attn_unit(const bf16_t* Qb, const bf16_t* Kb, const bf16_t* Vt, bf16_t* MIX, int b, int h, int qb, char* lds, int tid_in) {
;     ...
;     l_run = half_sum(l_run);
;     if (hh == 0) wsf[r] = 1.f / l_run;
;     LDS_WAIT();
;     bf16_t* op = MIX + (rowbase + q0 + 32 * wave) * DM + h * 64;
;     const int ob = 4 * hh * DM + r;
; #pragma unroll
;     for (int i = 0; i < 16; ++i) { const int q = crow(i, hh); const float f = wsf[q]; const int oi = ob + ((i & 3) + 8 * (i >> 2)) * DM; op[oi] = f2bf(o0[i] * f); op[oi + 32] = f2bf(o1[i] * f); }
.LBB0_444:
	s_or_b64 exec, exec, s[52:53]
	s_waitcnt lgkmcnt(0)
	ds_read_b128 v[190:193], v149
	ds_read_b128 v[194:197], v149 offset:32
	ds_read_b128 v[198:201], v149 offset:64
	ds_read_b128 v[212:215], v149 offset:96
	s_waitcnt lgkmcnt(0)
	v_lshlrev_b64 v[34:35], 11, v[146:147]
	v_lshl_or_b32 v36, v165, 12, v164
	v_lshl_add_u64 v[34:35], s[46:47], 0, v[34:35]
	v_ashrrev_i32_e32 v37, 31, v36
	v_mul_f32_e32 v18, v18, v190
	v_lshl_add_u64 v[34:35], v[36:37], 1, v[34:35]
	v_mul_f32_e32 v0, v2, v190
	v_cvt_pk_bf16_f32 v18, v18, v1
	global_store_short v[34:35], v18, off
	v_cvt_pk_bf16_f32 v0, v0, v1
	global_store_short v[34:35], v0, off offset:64
	s_movk_i32 s2, 0x1000
	s_add_i32 s37, s37, 1
	s_cmp_eq_u32 s37, 4
	v_mul_f32_e32 v0, v19, v191
	v_cvt_pk_bf16_f32 v0, v0, v1
	global_store_short v[34:35], v0, off offset:2048
	v_mul_f32_e32 v0, v3, v191
	v_cvt_pk_bf16_f32 v0, v0, v1
	global_store_short v[34:35], v0, off offset:2112
	v_add_co_u32_e32 v2, vcc, s2, v34
	s_movk_i32 s2, 0x5000
	v_mul_f32_e32 v0, v20, v192
	v_cvt_pk_bf16_f32 v0, v0, v1
	v_addc_co_u32_e32 v3, vcc, 0, v35, vcc
	global_store_short v[2:3], v0, off
	v_mul_f32_e32 v0, v4, v192
	v_cvt_pk_bf16_f32 v0, v0, v1
	global_store_short v[2:3], v0, off offset:64
	v_mul_f32_e32 v0, v21, v193
	v_cvt_pk_bf16_f32 v0, v0, v1
	global_store_short v[2:3], v0, off offset:2048
	v_mul_f32_e32 v0, v5, v193
	v_cvt_pk_bf16_f32 v0, v0, v1
	global_store_short v[2:3], v0, off offset:2112
	v_add_co_u32_e32 v2, vcc, s2, v34
	s_mov_b32 s2, 0x9000
	v_mul_f32_e32 v0, v22, v194
	v_cvt_pk_bf16_f32 v0, v0, v1
	v_addc_co_u32_e32 v3, vcc, 0, v35, vcc
	global_store_short v[2:3], v0, off offset:-4096
	v_mul_f32_e32 v0, v6, v194
	v_cvt_pk_bf16_f32 v0, v0, v1
	v_add_co_u32_e32 v4, vcc, s25, v34
	s_nop 1
	v_addc_co_u32_e32 v5, vcc, 0, v35, vcc
	global_store_short v[4:5], v0, off offset:64
	v_mul_f32_e32 v0, v23, v195
	v_cvt_pk_bf16_f32 v0, v0, v1
	global_store_short v[4:5], v0, off offset:2048
	v_mul_f32_e32 v0, v7, v195
	v_cvt_pk_bf16_f32 v0, v0, v1
	global_store_short v[4:5], v0, off offset:2112
	v_mul_f32_e32 v0, v24, v196
	v_cvt_pk_bf16_f32 v0, v0, v1
	global_store_short v[2:3], v0, off
	v_mul_f32_e32 v0, v8, v196
	v_cvt_pk_bf16_f32 v0, v0, v1
	global_store_short v[2:3], v0, off offset:64
	v_mul_f32_e32 v0, v25, v197
	v_cvt_pk_bf16_f32 v0, v0, v1
	global_store_short v[2:3], v0, off offset:2048
	v_mul_f32_e32 v0, v9, v197
	v_cvt_pk_bf16_f32 v0, v0, v1
	global_store_short v[2:3], v0, off offset:2112
	v_add_co_u32_e32 v2, vcc, s2, v34
	s_mov_b32 s2, 0x8000
	v_mul_f32_e32 v0, v26, v198
	v_cvt_pk_bf16_f32 v0, v0, v1
	v_addc_co_u32_e32 v3, vcc, 0, v35, vcc
	global_store_short v[2:3], v0, off offset:-4096
	v_mul_f32_e32 v0, v10, v198
	v_cvt_pk_bf16_f32 v0, v0, v1
	v_add_co_u32_e32 v4, vcc, s2, v34
	s_mov_b32 s2, 0xd000
	s_nop 0
	v_addc_co_u32_e32 v5, vcc, 0, v35, vcc
	global_store_short v[4:5], v0, off offset:64
	v_mul_f32_e32 v0, v27, v199
	v_cvt_pk_bf16_f32 v0, v0, v1
	global_store_short v[4:5], v0, off offset:2048
	v_mul_f32_e32 v0, v11, v199
	v_cvt_pk_bf16_f32 v0, v0, v1
	global_store_short v[4:5], v0, off offset:2112
	v_mul_f32_e32 v0, v28, v200
	v_cvt_pk_bf16_f32 v0, v0, v1
	global_store_short v[2:3], v0, off
	v_mul_f32_e32 v0, v12, v200
	v_cvt_pk_bf16_f32 v0, v0, v1
	global_store_short v[2:3], v0, off offset:64
	v_mul_f32_e32 v0, v29, v201
	v_cvt_pk_bf16_f32 v0, v0, v1
	global_store_short v[2:3], v0, off offset:2048
	v_mul_f32_e32 v0, v13, v201
	v_cvt_pk_bf16_f32 v0, v0, v1
	global_store_short v[2:3], v0, off offset:2112
	v_add_co_u32_e32 v2, vcc, s2, v34
	s_mov_b32 s2, 0xc000
	v_mul_f32_e32 v0, v30, v212
	v_cvt_pk_bf16_f32 v0, v0, v1
	v_addc_co_u32_e32 v3, vcc, 0, v35, vcc
	global_store_short v[2:3], v0, off offset:-4096
	v_mul_f32_e32 v0, v14, v212
	v_cvt_pk_bf16_f32 v0, v0, v1
	v_add_co_u32_e32 v4, vcc, s2, v34
	s_nop 1
	v_addc_co_u32_e32 v5, vcc, 0, v35, vcc
	global_store_short v[4:5], v0, off offset:64
	v_mul_f32_e32 v0, v31, v213
	v_cvt_pk_bf16_f32 v0, v0, v1
	global_store_short v[4:5], v0, off offset:2048
	v_mul_f32_e32 v0, v15, v213
	v_cvt_pk_bf16_f32 v0, v0, v1
	global_store_short v[4:5], v0, off offset:2112
	v_mul_f32_e32 v0, v32, v214
	v_cvt_pk_bf16_f32 v0, v0, v1
	global_store_short v[2:3], v0, off
	v_mul_f32_e32 v0, v16, v214
	v_cvt_pk_bf16_f32 v0, v0, v1
	global_store_short v[2:3], v0, off offset:64
	v_mul_f32_e32 v0, v33, v215
	v_cvt_pk_bf16_f32 v0, v0, v1
	global_store_short v[2:3], v0, off offset:2048
	v_mul_f32_e32 v0, v17, v215
	v_cvt_pk_bf16_f32 v0, v0, v1
	global_store_short v[2:3], v0, off offset:2112
	s_barrier
	s_cbranch_scc1 .LBB0_442
